# P0 adaLN accumulate: first two weight loads of each pass fetched during the previous pass (on v67)
# baseline (speedup 1.0000x reference)
; #define LAS __attribute__((address_space(3)))
; __device__ __forceinline__ float siluf_(float x) { return x * sigmoidf_(x); }
; __device__ __forceinline__ int lane_id_() { int l; asm volatile("v_mbcnt_lo_u32_b32 %0, -1, 0\n\tv_mbcnt_hi_u32_b32 %0, -1, %0" : "=v"(l)); return l; }
; #define F_c INF(1)
; #define F_ada_w INF(3)
; __device__ __forceinline__ void p0_prologue(const Ctx& F) {
;     ...
;     for (int it = F.bid; it < 192; it += F.G) {
;         const int l = it / 96, n0 = (it % 96) * 64;
;         LAS float* cs = (LAS float*)F.lds;
;         for (int e = (F.wid * 64 + lane_id_()); e < 32768; e += NTHREADS) { const int k = e >> 5, b = e & 31; cs[e] = siluf_(F_c[b * 1024 + k]); }
;         __syncthreads();
;         const int n = (F.wid * 64 + lane_id_()) & 63, kp = (F.wid * 64 + lane_id_()) >> 6;
;         float acc[32];
; #pragma unroll
;         for (int b = 0; b < 32; ++b) acc[b] = 0.f;
;         const float* wp = F_ada_w + ((size_t)l * 1024 + kp * 128) * 6144 + n0 + n;
;         for (int k8 = 0; k8 < 128; k8 += 8) {
;             float wv[8];
; #pragma unroll
;             for (int u = 0; u < 8; ++u) wv[u] = wp[(size_t)(k8 + u) * 6144];
; #pragma unroll
;             for (int u = 0; u < 8; ++u) { const float w = wv[u]; const LAS f32x4* cr = (const LAS f32x4*)(cs + (kp * 128 + k8 + u) * 32);
; #pragma unroll
;                 for (int b4 = 0; b4 < 8; ++b4) { const f32x4 cv = cr[b4]; acc[4 * b4] += cv[0] * w; acc[4 * b4 + 1] += cv[1] * w; acc[4 * b4 + 2] += cv[2] * w; acc[4 * b4 + 3] += cv[3] * w; } }
.LBB0_11:
	s_or_b64 exec, exec, s[10:11]
	s_mul_hi_i32 s10, s31, 0x2aaaaaab
	s_lshr_b32 s11, s10, 31
	s_ashr_i32 s10, s10, 4
	s_add_i32 s10, s10, s11
	s_mul_i32 s11, s10, 0x60
	s_sub_i32 s11, s31, s11
	s_lshl_b32 s14, s11, 6
	s_ashr_i32 s15, s14, 31
	s_waitcnt lgkmcnt(0)
	s_barrier
	v_mbcnt_lo_u32_b32 v2, -1, 0
	v_mbcnt_hi_u32_b32 v2, -1, v2
	v_mbcnt_lo_u32_b32 v4, -1, 0
	v_mbcnt_hi_u32_b32 v4, -1, v4
	s_ashr_i32 s11, s10, 31
	s_mul_i32 s36, s10, 0x1800000
	s_lshl_b64 s[16:17], s[14:15], 2
	v_add_u32_e32 v4, s0, v4
	s_load_dwordx2 s[34:35], s[12:13], 0x18
	s_mul_hi_i32 s33, s10, 0x1800000
	s_add_u32 s36, s16, s36
	v_ashrrev_i32_e32 v47, 6, v4
	s_addc_u32 s37, s17, s33
	v_and_b32_e32 v46, 63, v2
	v_lshlrev_b32_e32 v2, 7, v47
	v_mov_b64_e32 v[4:5], s[36:37]
	v_mad_i64_i32 v[4:5], s[36:37], v2, s23, v[4:5]
	v_lshl_or_b32 v4, v46, 2, v4
	s_waitcnt lgkmcnt(0)
	v_lshl_add_u64 v[4:5], s[34:35], 0, v[4:5]
	v_mov_b32_e32 v8, 0
	v_lshl_add_u32 v48, v47, 14, 0
	v_lshl_add_u64 v[4:5], v[4:5], 0, s[4:5]
	s_mov_b32 s15, -8
	v_mov_b32_e32 v9, v8
	v_mov_b32_e32 v42, v8
	v_mov_b32_e32 v43, v8
	v_mov_b32_e32 v44, v8
	v_mov_b32_e32 v45, v8
	v_mov_b32_e32 v32, v8
	v_mov_b32_e32 v33, v8
	v_mov_b32_e32 v34, v8
	v_mov_b32_e32 v35, v8
	v_mov_b32_e32 v24, v8
	v_mov_b32_e32 v25, v8
	v_mov_b32_e32 v26, v8
	v_mov_b32_e32 v27, v8
	v_mov_b32_e32 v18, v8
	v_mov_b32_e32 v19, v8
	v_mov_b32_e32 v20, v8
	v_mov_b32_e32 v21, v8
	v_mov_b32_e32 v12, v8
	v_mov_b32_e32 v13, v8
	v_mov_b32_e32 v14, v8
	v_mov_b32_e32 v15, v8
	v_mov_b32_e32 v36, v8
	v_mov_b32_e32 v37, v8
	v_mov_b32_e32 v38, v8
	v_mov_b32_e32 v39, v8
	v_mov_b32_e32 v28, v8
	v_mov_b32_e32 v29, v8
	v_mov_b32_e32 v30, v8
	v_mov_b32_e32 v31, v8
	v_mov_b32_e32 v16, v8
	v_mov_b32_e32 v17, v8
	v_add_co_u32_e32 v112, vcc, s24, v4
	s_nop 1
	v_addc_co_u32_e32 v113, vcc, -1, v5, vcc
	v_add_co_u32_e32 v114, vcc, s25, v4
	s_nop 1
	v_addc_co_u32_e32 v115, vcc, -1, v5, vcc
	global_load_dword v110, v[112:113], off
	global_load_dword v111, v[114:115], off
.LBB0_12:
	v_add_co_u32_e32 v6, vcc, s24, v4
	ds_read_b128 v[50:53], v48
	ds_read_b128 v[54:57], v48 offset:16
	v_addc_co_u32_e32 v7, vcc, -1, v5, vcc
	v_add_co_u32_e32 v10, vcc, s25, v4
	s_add_i32 s15, s15, 8
	s_nop 0
	v_addc_co_u32_e32 v11, vcc, -1, v5, vcc
	v_add_co_u32_e32 v62, vcc, s26, v4
	ds_read_b128 v[58:61], v48 offset:32
	s_nop 0
	v_addc_co_u32_e32 v63, vcc, -1, v5, vcc
	v_add_co_u32_e32 v64, vcc, s27, v4
	s_cmpk_gt_u32 s15, 0x77
	s_nop 0
	v_addc_co_u32_e32 v65, vcc, -1, v5, vcc
	v_add_co_u32_e32 v66, vcc, s28, v4
	s_waitcnt vmcnt(0) lgkmcnt(0)
	v_mov_b32_e32 v40, v110
	v_mov_b32_e32 v41, v111
	v_pk_fma_f32 v[42:43], v[40:41], v[50:51], v[42:43] op_sel_hi:[0,1,1]
	v_addc_co_u32_e32 v67, vcc, -1, v5, vcc
	v_add_co_u32_e32 v68, vcc, s29, v4
	v_pk_fma_f32 v[44:45], v[40:41], v[52:53], v[44:45] op_sel_hi:[0,1,1]
	s_nop 0
	v_addc_co_u32_e32 v69, vcc, -1, v5, vcc
	v_add_co_u32_e32 v70, vcc, s30, v4
	v_pk_fma_f32 v[54:55], v[40:41], v[54:55], v[32:33] op_sel_hi:[0,1,1]
	s_nop 0
	v_addc_co_u32_e32 v71, vcc, -1, v5, vcc
	global_load_dword v22, v[62:63], off
	global_load_dword v23, v[64:65], off
	global_load_dword v10, v[66:67], off
	global_load_dword v11, v[68:69], off
	global_load_dword v6, v[70:71], off
	global_load_dword v2, v[4:5], off
	ds_read_b128 v[50:53], v48 offset:48
	v_pk_fma_f32 v[56:57], v[40:41], v[56:57], v[34:35] op_sel_hi:[0,1,1]
	ds_read_b128 v[32:35], v48 offset:64
	v_pk_fma_f32 v[58:59], v[40:41], v[58:59], v[24:25] op_sel_hi:[0,1,1]
	v_pk_fma_f32 v[60:61], v[40:41], v[60:61], v[26:27] op_sel_hi:[0,1,1]
	ds_read_b128 v[24:27], v48 offset:80
	s_waitcnt lgkmcnt(0)
	v_pk_fma_f32 v[50:51], v[40:41], v[50:51], v[18:19] op_sel_hi:[0,1,1]
	v_pk_fma_f32 v[52:53], v[40:41], v[52:53], v[20:21] op_sel_hi:[0,1,1]
	ds_read_b128 v[18:21], v48 offset:96
	v_pk_fma_f32 v[62:63], v[40:41], v[32:33], v[12:13] op_sel_hi:[0,1,1]
	v_pk_fma_f32 v[64:65], v[40:41], v[34:35], v[14:15] op_sel_hi:[0,1,1]
	ds_read_b128 v[32:35], v48 offset:112
	ds_read_b128 v[12:15], v48 offset:128
	s_waitcnt lgkmcnt(0)
	v_pk_fma_f32 v[28:29], v[40:41], v[18:19], v[28:29] op_sel_hi:[0,1,1]
	v_pk_fma_f32 v[30:31], v[40:41], v[20:21], v[30:31] op_sel_hi:[0,1,1]
	ds_read_b128 v[18:21], v48 offset:144
	v_mov_b32_e32 v66, v41
	v_pk_fma_f32 v[42:43], v[66:67], v[12:13], v[42:43] op_sel_hi:[0,1,1]
	v_pk_fma_f32 v[44:45], v[66:67], v[14:15], v[44:45] op_sel_hi:[0,1,1]
	ds_read_b128 v[12:15], v48 offset:160
	s_waitcnt lgkmcnt(0)
	v_pk_fma_f32 v[54:55], v[66:67], v[18:19], v[54:55] op_sel_hi:[0,1,1]
	v_pk_fma_f32 v[56:57], v[66:67], v[20:21], v[56:57] op_sel_hi:[0,1,1]
	ds_read_b128 v[18:21], v48 offset:176
	v_pk_fma_f32 v[36:37], v[40:41], v[24:25], v[36:37] op_sel_hi:[0,1,1]
	v_pk_fma_f32 v[38:39], v[40:41], v[26:27], v[38:39] op_sel_hi:[0,1,1]
	v_pk_fma_f32 v[58:59], v[66:67], v[12:13], v[58:59] op_sel_hi:[0,1,1]
	v_pk_fma_f32 v[60:61], v[66:67], v[14:15], v[60:61] op_sel_hi:[0,1,1]
	ds_read_b128 v[12:15], v48 offset:192
	s_waitcnt lgkmcnt(0)
	v_pk_fma_f32 v[50:51], v[66:67], v[18:19], v[50:51] op_sel_hi:[0,1,1]
	v_pk_fma_f32 v[52:53], v[66:67], v[20:21], v[52:53] op_sel_hi:[0,1,1]
	ds_read_b128 v[18:21], v48 offset:208
	ds_read_b128 v[24:27], v48 offset:240
	v_pk_fma_f32 v[62:63], v[66:67], v[12:13], v[62:63] op_sel_hi:[0,1,1]
	v_pk_fma_f32 v[64:65], v[66:67], v[14:15], v[64:65] op_sel_hi:[0,1,1]
	v_pk_fma_f32 v[32:33], v[40:41], v[32:33], v[16:17] op_sel_hi:[0,1,1]
	v_mul_f32_e32 v14, v40, v34
	s_waitcnt lgkmcnt(0)
	v_mul_f32_e32 v12, v41, v26
	v_mov_b32_e32 v26, v35
	v_pk_fma_f32 v[34:35], v[66:67], v[18:19], v[36:37] op_sel_hi:[0,1,1]
	ds_read_b128 v[16:19], v48 offset:224
	v_pk_mul_f32 v[36:37], v[40:41], v[26:27]
	v_pk_fma_f32 v[32:33], v[66:67], v[24:25], v[32:33] op_sel_hi:[0,1,1]
	ds_read_b128 v[24:27], v48 offset:272
	v_pk_fma_f32 v[20:21], v[66:67], v[20:21], v[38:39] op_sel_hi:[0,1,1]
	s_waitcnt lgkmcnt(0)
	v_pk_fma_f32 v[28:29], v[66:67], v[16:17], v[28:29] op_sel_hi:[0,1,1]
	v_pk_fma_f32 v[30:31], v[66:67], v[18:19], v[30:31] op_sel_hi:[0,1,1]
	ds_read_b128 v[16:19], v48 offset:256
	v_mov_b32_e32 v15, v36
	v_mov_b32_e32 v13, v37
	v_pk_add_f32 v[8:9], v[8:9], v[14:15]
	v_lshl_add_u64 v[4:5], v[4:5], 0, s[8:9]
	v_pk_add_f32 v[12:13], v[8:9], v[12:13]
	s_waitcnt vmcnt(0) lgkmcnt(0)
	s_cbranch_scc1 .Lada_nopf
	v_add_co_u32_e32 v112, vcc, s24, v4
	s_nop 1
	v_addc_co_u32_e32 v113, vcc, -1, v5, vcc
	v_add_co_u32_e32 v114, vcc, s25, v4
	s_nop 1
	v_addc_co_u32_e32 v115, vcc, -1, v5, vcc
	global_load_dword v110, v[112:113], off
	global_load_dword v111, v[114:115], off
; #define LAS __attribute__((address_space(3)))
; __device__ __forceinline__ void p0_prologue(const Ctx& F) {
;     ...
;             for (int u = 0; u < 8; ++u) wv[u] = wp[(size_t)(k8 + u) * 6144];
; #pragma unroll
;             for (int u = 0; u < 8; ++u) { const float w = wv[u]; const LAS f32x4* cr = (const LAS f32x4*)(cs + (kp * 128 + k8 + u) * 32);
; #pragma unroll
;                 for (int b4 = 0; b4 < 8; ++b4) { const f32x4 cv = cr[b4]; acc[4 * b4] += cv[0] * w; acc[4 * b4 + 1] += cv[1] * w; acc[4 * b4 + 2] += cv[2] * w; acc[4 * b4 + 3] += cv[3] * w; } }
.Lada_nopf:
	v_pk_fma_f32 v[38:39], v[22:23], v[16:17], v[42:43] op_sel_hi:[0,1,1]
	v_pk_fma_f32 v[40:41], v[22:23], v[18:19], v[44:45] op_sel_hi:[0,1,1]
	ds_read_b128 v[16:19], v48 offset:288
	v_pk_fma_f32 v[42:43], v[22:23], v[24:25], v[54:55] op_sel_hi:[0,1,1]
	v_pk_fma_f32 v[44:45], v[22:23], v[26:27], v[56:57] op_sel_hi:[0,1,1]
	ds_read_b128 v[24:27], v48 offset:304
	v_mov_b32_e32 v66, v23
	s_waitcnt lgkmcnt(1)
	v_pk_fma_f32 v[54:55], v[22:23], v[16:17], v[58:59] op_sel_hi:[0,1,1]
	v_pk_fma_f32 v[56:57], v[22:23], v[18:19], v[60:61] op_sel_hi:[0,1,1]
	ds_read_b128 v[16:19], v48 offset:320
	s_waitcnt lgkmcnt(1)
	v_pk_fma_f32 v[50:51], v[22:23], v[24:25], v[50:51] op_sel_hi:[0,1,1]
	v_pk_fma_f32 v[52:53], v[22:23], v[26:27], v[52:53] op_sel_hi:[0,1,1]
	ds_read_b128 v[24:27], v48 offset:336
	s_waitcnt lgkmcnt(1)
	v_pk_fma_f32 v[58:59], v[22:23], v[16:17], v[62:63] op_sel_hi:[0,1,1]
	v_pk_fma_f32 v[60:61], v[22:23], v[18:19], v[64:65] op_sel_hi:[0,1,1]
	ds_read_b128 v[16:19], v48 offset:352
	s_waitcnt lgkmcnt(1)
	v_pk_fma_f32 v[34:35], v[22:23], v[24:25], v[34:35] op_sel_hi:[0,1,1]
	v_pk_fma_f32 v[20:21], v[22:23], v[26:27], v[20:21] op_sel_hi:[0,1,1]
	ds_read_b128 v[24:27], v48 offset:368
	s_waitcnt lgkmcnt(1)
	v_pk_fma_f32 v[62:63], v[22:23], v[16:17], v[28:29] op_sel_hi:[0,1,1]
	v_pk_fma_f32 v[64:65], v[22:23], v[18:19], v[30:31] op_sel_hi:[0,1,1]
	ds_read_b128 v[16:19], v48 offset:384
	ds_read_b128 v[28:31], v48 offset:400
	s_waitcnt lgkmcnt(1)
	v_pk_fma_f32 v[38:39], v[66:67], v[16:17], v[38:39] op_sel_hi:[0,1,1]
	v_pk_fma_f32 v[40:41], v[66:67], v[18:19], v[40:41] op_sel_hi:[0,1,1]
	s_waitcnt lgkmcnt(0)
	v_pk_fma_f32 v[42:43], v[66:67], v[28:29], v[42:43] op_sel_hi:[0,1,1]
	v_pk_fma_f32 v[44:45], v[66:67], v[30:31], v[44:45] op_sel_hi:[0,1,1]
	ds_read_b128 v[16:19], v48 offset:416
	ds_read_b128 v[28:31], v48 offset:432
	s_waitcnt lgkmcnt(1)
	v_pk_fma_f32 v[54:55], v[66:67], v[16:17], v[54:55] op_sel_hi:[0,1,1]
	v_pk_fma_f32 v[56:57], v[66:67], v[18:19], v[56:57] op_sel_hi:[0,1,1]
	s_waitcnt lgkmcnt(0)
	v_pk_fma_f32 v[50:51], v[66:67], v[28:29], v[50:51] op_sel_hi:[0,1,1]
	v_pk_fma_f32 v[52:53], v[66:67], v[30:31], v[52:53] op_sel_hi:[0,1,1]
	ds_read_b128 v[16:19], v48 offset:448
	ds_read_b128 v[28:31], v48 offset:464
	s_waitcnt lgkmcnt(1)
	v_pk_fma_f32 v[58:59], v[66:67], v[16:17], v[58:59] op_sel_hi:[0,1,1]
	v_pk_fma_f32 v[60:61], v[66:67], v[18:19], v[60:61] op_sel_hi:[0,1,1]
	s_waitcnt lgkmcnt(0)
	v_pk_fma_f32 v[34:35], v[66:67], v[28:29], v[34:35] op_sel_hi:[0,1,1]
	v_pk_fma_f32 v[68:69], v[66:67], v[30:31], v[20:21] op_sel_hi:[0,1,1]
	ds_read_b128 v[16:19], v48 offset:480
	ds_read_b128 v[28:31], v48 offset:496
	s_waitcnt lgkmcnt(1)
	v_pk_fma_f32 v[62:63], v[66:67], v[16:17], v[62:63] op_sel_hi:[0,1,1]
	s_waitcnt lgkmcnt(0)
	v_mul_f32_e32 v70, v23, v30
	v_mov_b32_e32 v30, v27
	v_pk_fma_f32 v[16:17], v[22:23], v[24:25], v[32:33] op_sel_hi:[0,1,1]
	v_pk_fma_f32 v[64:65], v[66:67], v[18:19], v[64:65] op_sel_hi:[0,1,1]
	v_mul_f32_e32 v32, v22, v26
	v_pk_mul_f32 v[72:73], v[22:23], v[30:31]
	v_pk_fma_f32 v[66:67], v[66:67], v[28:29], v[16:17] op_sel_hi:[0,1,1]
	ds_read_b128 v[16:19], v48 offset:512
	ds_read_b128 v[20:23], v48 offset:528
	v_mov_b32_e32 v33, v72
	v_mov_b32_e32 v71, v73
	v_pk_add_f32 v[12:13], v[12:13], v[32:33]
	s_waitcnt lgkmcnt(1)
	v_pk_fma_f32 v[28:29], v[10:11], v[16:17], v[38:39] op_sel_hi:[0,1,1]
	v_pk_fma_f32 v[30:31], v[10:11], v[18:19], v[40:41] op_sel_hi:[0,1,1]
	s_waitcnt lgkmcnt(0)
	v_pk_fma_f32 v[38:39], v[10:11], v[20:21], v[42:43] op_sel_hi:[0,1,1]
	v_pk_fma_f32 v[40:41], v[10:11], v[22:23], v[44:45] op_sel_hi:[0,1,1]
	ds_read_b128 v[16:19], v48 offset:544
	ds_read_b128 v[20:23], v48 offset:560
	v_pk_add_f32 v[70:71], v[12:13], v[70:71]
	s_waitcnt lgkmcnt(1)
	v_pk_fma_f32 v[42:43], v[10:11], v[16:17], v[54:55] op_sel_hi:[0,1,1]
	v_pk_fma_f32 v[44:45], v[10:11], v[18:19], v[56:57] op_sel_hi:[0,1,1]
	s_waitcnt lgkmcnt(0)
	v_pk_fma_f32 v[50:51], v[10:11], v[20:21], v[50:51] op_sel_hi:[0,1,1]
	v_pk_fma_f32 v[52:53], v[10:11], v[22:23], v[52:53] op_sel_hi:[0,1,1]
	ds_read_b128 v[16:19], v48 offset:576
	ds_read_b128 v[20:23], v48 offset:592
	s_waitcnt lgkmcnt(1)
	v_pk_fma_f32 v[54:55], v[10:11], v[16:17], v[58:59] op_sel_hi:[0,1,1]
	v_pk_fma_f32 v[56:57], v[10:11], v[18:19], v[60:61] op_sel_hi:[0,1,1]
	ds_read_b128 v[16:19], v48 offset:608
	ds_read_b128 v[24:27], v48 offset:624
	s_waitcnt lgkmcnt(2)
	v_pk_fma_f32 v[34:35], v[10:11], v[20:21], v[34:35] op_sel_hi:[0,1,1]
	v_pk_fma_f32 v[58:59], v[10:11], v[22:23], v[68:69] op_sel_hi:[0,1,1]
	s_waitcnt lgkmcnt(1)
	v_pk_fma_f32 v[60:61], v[10:11], v[16:17], v[62:63] op_sel_hi:[0,1,1]
	v_pk_fma_f32 v[62:63], v[10:11], v[18:19], v[64:65] op_sel_hi:[0,1,1]
	ds_read_b128 v[16:19], v48 offset:640
	ds_read_b128 v[20:23], v48 offset:656
	v_mov_b32_e32 v64, v11
	s_waitcnt lgkmcnt(1)
	v_pk_fma_f32 v[68:69], v[64:65], v[16:17], v[28:29] op_sel_hi:[0,1,1]
	v_pk_fma_f32 v[74:75], v[64:65], v[18:19], v[30:31] op_sel_hi:[0,1,1]
	s_waitcnt lgkmcnt(0)
	v_pk_fma_f32 v[38:39], v[64:65], v[20:21], v[38:39] op_sel_hi:[0,1,1]
	v_pk_fma_f32 v[76:77], v[64:65], v[22:23], v[40:41] op_sel_hi:[0,1,1]
	ds_read_b128 v[16:19], v48 offset:672
	ds_read_b128 v[20:23], v48 offset:688
	v_mul_f32_e32 v40, v10, v26
	s_waitcnt lgkmcnt(1)
	v_pk_fma_f32 v[42:43], v[64:65], v[16:17], v[42:43] op_sel_hi:[0,1,1]
	v_pk_fma_f32 v[44:45], v[64:65], v[18:19], v[44:45] op_sel_hi:[0,1,1]
	s_waitcnt lgkmcnt(0)
	v_pk_fma_f32 v[50:51], v[64:65], v[20:21], v[50:51] op_sel_hi:[0,1,1]
	v_pk_fma_f32 v[52:53], v[64:65], v[22:23], v[52:53] op_sel_hi:[0,1,1]
	ds_read_b128 v[16:19], v48 offset:704
	ds_read_b128 v[20:23], v48 offset:720
	s_waitcnt lgkmcnt(1)
; #define LAS __attribute__((address_space(3)))
; __device__ __forceinline__ void p0_prologue(const Ctx& F) {
;     ...
;             for (int u = 0; u < 8; ++u) wv[u] = wp[(size_t)(k8 + u) * 6144];
; #pragma unroll
;             for (int u = 0; u < 8; ++u) { const float w = wv[u]; const LAS f32x4* cr = (const LAS f32x4*)(cs + (kp * 128 + k8 + u) * 32);
; #pragma unroll
;                 for (int b4 = 0; b4 < 8; ++b4) { const f32x4 cv = cr[b4]; acc[4 * b4] += cv[0] * w; acc[4 * b4 + 1] += cv[1] * w; acc[4 * b4 + 2] += cv[2] * w; acc[4 * b4 + 3] += cv[3] * w; } }
;         }
;         __syncthreads();
;         LAS float* red = (LAS float*)F.lds;
; #pragma unroll
;         for (int b = 0; b < 32; ++b) red[(kp * 32 + b) * 64 + n] = acc[b];
	v_pk_fma_f32 v[54:55], v[64:65], v[16:17], v[54:55] op_sel_hi:[0,1,1]
	v_pk_fma_f32 v[56:57], v[64:65], v[18:19], v[56:57] op_sel_hi:[0,1,1]
	ds_read_b128 v[16:19], v48 offset:736
	ds_read_b128 v[28:31], v48 offset:752
	s_waitcnt lgkmcnt(2)
	v_pk_fma_f32 v[20:21], v[64:65], v[20:21], v[34:35] op_sel_hi:[0,1,1]
	v_pk_fma_f32 v[34:35], v[64:65], v[22:23], v[58:59] op_sel_hi:[0,1,1]
	ds_read_b128 v[12:15], v48 offset:912
	s_waitcnt lgkmcnt(2)
	v_pk_fma_f32 v[58:59], v[64:65], v[16:17], v[60:61] op_sel_hi:[0,1,1]
	v_pk_fma_f32 v[16:17], v[10:11], v[24:25], v[66:67] op_sel_hi:[0,1,1]
	v_pk_fma_f32 v[60:61], v[64:65], v[18:19], v[62:63] op_sel_hi:[0,1,1]
	s_waitcnt lgkmcnt(1)
	v_mul_f32_e32 v22, v11, v30
	v_mov_b32_e32 v30, v27
	v_pk_fma_f32 v[28:29], v[64:65], v[28:29], v[16:17] op_sel_hi:[0,1,1]
	ds_read_b128 v[16:19], v48 offset:768
	ds_read_b128 v[24:27], v48 offset:784
	v_pk_mul_f32 v[10:11], v[10:11], v[30:31]
	s_waitcnt lgkmcnt(1)
	v_pk_fma_f32 v[30:31], v[6:7], v[16:17], v[68:69] op_sel_hi:[0,1,1]
	v_pk_fma_f32 v[36:37], v[6:7], v[18:19], v[74:75] op_sel_hi:[0,1,1]
	ds_read_b128 v[16:19], v48 offset:800
	s_waitcnt lgkmcnt(1)
	v_pk_fma_f32 v[38:39], v[6:7], v[24:25], v[38:39] op_sel_hi:[0,1,1]
	v_pk_fma_f32 v[62:63], v[6:7], v[26:27], v[76:77] op_sel_hi:[0,1,1]
	ds_read_b128 v[24:27], v48 offset:816
	v_mov_b32_e32 v41, v10
	v_mov_b32_e32 v23, v11
	s_waitcnt lgkmcnt(1)
	v_pk_fma_f32 v[64:65], v[6:7], v[16:17], v[42:43] op_sel_hi:[0,1,1]
	v_pk_fma_f32 v[66:67], v[6:7], v[18:19], v[44:45] op_sel_hi:[0,1,1]
	ds_read_b128 v[16:19], v48 offset:832
	s_waitcnt lgkmcnt(1)
	v_pk_fma_f32 v[68:69], v[6:7], v[24:25], v[50:51] op_sel_hi:[0,1,1]
	v_pk_fma_f32 v[72:73], v[6:7], v[26:27], v[52:53] op_sel_hi:[0,1,1]
	ds_read_b128 v[24:27], v48 offset:848
	ds_read_b128 v[8:11], v48 offset:896
	s_waitcnt lgkmcnt(2)
	v_pk_fma_f32 v[54:55], v[6:7], v[16:17], v[54:55] op_sel_hi:[0,1,1]
	v_pk_fma_f32 v[56:57], v[6:7], v[18:19], v[56:57] op_sel_hi:[0,1,1]
	ds_read_b128 v[16:19], v48 offset:864
	s_waitcnt lgkmcnt(2)
	v_pk_fma_f32 v[74:75], v[6:7], v[24:25], v[20:21] op_sel_hi:[0,1,1]
	v_pk_fma_f32 v[76:77], v[6:7], v[26:27], v[34:35] op_sel_hi:[0,1,1]
	ds_read_b128 v[24:27], v48 offset:880
	ds_read_b128 v[50:53], v48 offset:1008
	s_waitcnt lgkmcnt(3)
	v_pk_fma_f32 v[42:43], v[2:3], v[8:9], v[30:31] op_sel_hi:[0,1,1]
	v_pk_fma_f32 v[44:45], v[2:3], v[10:11], v[36:37] op_sel_hi:[0,1,1]
	ds_read_b128 v[8:11], v48 offset:928
	s_waitcnt lgkmcnt(3)
	v_pk_fma_f32 v[16:17], v[6:7], v[16:17], v[58:59] op_sel_hi:[0,1,1]
	v_pk_fma_f32 v[58:59], v[6:7], v[18:19], v[60:61] op_sel_hi:[0,1,1]
	s_waitcnt lgkmcnt(2)
	v_mul_f32_e32 v60, v6, v26
	s_waitcnt lgkmcnt(1)
	v_mul_f32_e32 v78, v2, v52
	v_mov_b32_e32 v52, v27
	v_pk_fma_f32 v[80:81], v[6:7], v[24:25], v[28:29] op_sel_hi:[0,1,1]
	v_pk_fma_f32 v[32:33], v[2:3], v[12:13], v[38:39] op_sel_hi:[0,1,1]
	v_pk_fma_f32 v[34:35], v[2:3], v[14:15], v[62:63] op_sel_hi:[0,1,1]
	ds_read_b128 v[12:15], v48 offset:944
	s_waitcnt lgkmcnt(1)
	v_pk_fma_f32 v[24:25], v[2:3], v[8:9], v[64:65] op_sel_hi:[0,1,1]
	v_pk_fma_f32 v[26:27], v[2:3], v[10:11], v[66:67] op_sel_hi:[0,1,1]
	ds_read_b128 v[8:11], v48 offset:960
	ds_read_b128 v[28:31], v48 offset:976
	s_waitcnt lgkmcnt(2)
	v_pk_fma_f32 v[18:19], v[2:3], v[12:13], v[68:69] op_sel_hi:[0,1,1]
	v_pk_fma_f32 v[20:21], v[2:3], v[14:15], v[72:73] op_sel_hi:[0,1,1]
	v_mov_b32_e32 v7, v2
	s_waitcnt lgkmcnt(1)
	v_pk_fma_f32 v[12:13], v[2:3], v[8:9], v[54:55] op_sel_hi:[0,1,1]
	v_pk_fma_f32 v[14:15], v[2:3], v[10:11], v[56:57] op_sel_hi:[0,1,1]
	ds_read_b128 v[8:11], v48 offset:992
	s_waitcnt lgkmcnt(1)
	v_pk_fma_f32 v[36:37], v[2:3], v[28:29], v[74:75] op_sel_hi:[0,1,1]
	v_pk_mul_f32 v[6:7], v[6:7], v[52:53]
	v_add_u32_e32 v48, 0x400, v48
	v_mov_b32_e32 v61, v6
	s_waitcnt lgkmcnt(0)
	v_pk_fma_f32 v[28:29], v[2:3], v[8:9], v[16:17] op_sel_hi:[0,1,1]
	v_pk_add_f32 v[8:9], v[70:71], v[40:41]
	v_mov_b32_e32 v79, v7
	v_pk_add_f32 v[8:9], v[8:9], v[22:23]
	v_pk_fma_f32 v[38:39], v[2:3], v[30:31], v[76:77] op_sel_hi:[0,1,1]
	v_pk_add_f32 v[6:7], v[8:9], v[60:61]
	v_pk_fma_f32 v[30:31], v[2:3], v[10:11], v[58:59] op_sel_hi:[0,1,1]
	v_pk_fma_f32 v[16:17], v[2:3], v[50:51], v[80:81] op_sel_hi:[0,1,1]
	v_pk_add_f32 v[8:9], v[6:7], v[78:79]
	s_cbranch_scc0 .LBB0_12
	v_lshlrev_b32_e32 v2, 13, v47
	v_lshlrev_b32_e32 v4, 2, v46
	v_add3_u32 v2, 0, v2, v4
	s_add_u32 s34, s46, s16
	s_barrier
	ds_write2st64_b32 v2, v42, v43 offset1:1
	ds_write2st64_b32 v2, v44, v45 offset0:2 offset1:3
	ds_write2st64_b32 v2, v32, v33 offset0:4 offset1:5
	ds_write2st64_b32 v2, v34, v35 offset0:6 offset1:7
	ds_write2st64_b32 v2, v24, v25 offset0:8 offset1:9
	ds_write2st64_b32 v2, v26, v27 offset0:10 offset1:11
	ds_write2st64_b32 v2, v18, v19 offset0:12 offset1:13
	ds_write2st64_b32 v2, v20, v21 offset0:14 offset1:15
	ds_write2st64_b32 v2, v12, v13 offset0:16 offset1:17
	ds_write2st64_b32 v2, v14, v15 offset0:18 offset1:19
	ds_write2st64_b32 v2, v36, v37 offset0:20 offset1:21
	ds_write2st64_b32 v2, v38, v39 offset0:22 offset1:23
	ds_write2st64_b32 v2, v28, v29 offset0:24 offset1:25
	ds_write2st64_b32 v2, v30, v31 offset0:26 offset1:27
	ds_write2st64_b32 v2, v16, v17 offset0:28 offset1:29
	ds_write2st64_b32 v2, v8, v9 offset0:30 offset1:31
	s_waitcnt lgkmcnt(0)
	s_barrier
; __device__ __forceinline__ int lane_id_() { int l; asm volatile("v_mbcnt_lo_u32_b32 %0, -1, 0\n\tv_mbcnt_hi_u32_b32 %0, -1, %0" : "=v"(l)); return l; }
; #define F_ada_b INF(4)
; __device__ __forceinline__ void p0_prologue(const Ctx& F) {
;     ...
; #pragma unroll
;         for (int i = 0; i < 4; ++i) { const int o = (F.wid * 64 + lane_id_()) + NTHREADS * i, b = o >> 6, nn = o & 63; float s = F_ada_b[l * 6144 + n0 + nn];
; #pragma unroll
;             for (int p = 0; p < 8; ++p) s += red[(p * 32 + b) * 64 + nn];
;             mod[((size_t)l * 32 + b) * 6144 + n0 + nn] = s; }
;         __syncthreads();
	s_addc_u32 s35, s47, s17
	v_mbcnt_lo_u32_b32 v2, -1, 0
	v_mbcnt_hi_u32_b32 v2, -1, v2
	s_load_dwordx2 s[16:17], s[12:13], 0x20
	s_mul_i32 s15, s10, 0x1800
	s_add_i32 s33, s15, s14
	v_and_b32_e32 v6, 63, v2
	v_or_b32_e32 v4, s33, v6
	v_ashrrev_i32_e32 v5, 31, v4
	s_waitcnt lgkmcnt(0)
	v_lshl_add_u64 v[4:5], v[4:5], 2, s[16:17]
	flat_load_dword v18, v[4:5]
	v_add_u32_e32 v7, s0, v2
	v_and_b32_e32 v8, 0x3fffffc0, v7
	v_lshlrev_b32_e32 v2, 2, v6
	v_ashrrev_i32_e32 v6, 6, v7
	s_lshl_b64 s[10:11], s[10:11], 5
	v_lshlrev_b32_e32 v8, 2, v8
	v_ashrrev_i32_e32 v7, 31, v6
	v_mov_b64_e32 v[4:5], s[34:35]
	v_add3_u32 v14, 0, v8, v2
	v_lshl_add_u64 v[6:7], s[10:11], 0, v[6:7]
	ds_read2st64_b32 v[8:9], v14 offset1:32
	ds_read2st64_b32 v[10:11], v14 offset0:64 offset1:96
	ds_read2st64_b32 v[12:13], v14 offset0:128 offset1:160
	ds_read2st64_b32 v[14:15], v14 offset0:192 offset1:224
	v_mad_u64_u32 v[16:17], s[14:15], v6, s23, v[4:5]
	v_mad_i32_i24 v17, v7, s23, v17
	v_lshl_add_u64 v[6:7], v[16:17], 0, v[2:3]
	s_add_i32 s31, s31, s90
	s_cmpk_gt_i32 s31, 0xbf
	s_waitcnt vmcnt(0) lgkmcnt(0)
	v_add_f32_e32 v2, v18, v8
	v_add_f32_e32 v2, v2, v9
	v_add_f32_e32 v2, v2, v10
	v_add_f32_e32 v2, v2, v11
	v_add_f32_e32 v2, v2, v12
	v_add_f32_e32 v2, v2, v13
	v_add_f32_e32 v2, v2, v14
	v_add_f32_e32 v2, v2, v15
	global_store_dword v[6:7], v2, off
	v_mbcnt_lo_u32_b32 v2, -1, 0
	v_mbcnt_hi_u32_b32 v2, -1, v2
	s_nop 0
	v_and_b32_e32 v8, 63, v2
	v_or_b32_e32 v6, s33, v8
	v_ashrrev_i32_e32 v7, 31, v6
	v_lshl_add_u64 v[6:7], v[6:7], 2, s[16:17]
	flat_load_dword v18, v[6:7]
	v_add_u32_e32 v6, s1, v2
	v_and_b32_e32 v7, 0x3fffffc0, v6
	v_ashrrev_i32_e32 v6, 6, v6
	v_lshlrev_b32_e32 v2, 2, v8
	v_lshlrev_b32_e32 v8, 2, v7
	v_ashrrev_i32_e32 v7, 31, v6
	v_add3_u32 v14, 0, v8, v2
	v_lshl_add_u64 v[6:7], s[10:11], 0, v[6:7]
	ds_read2st64_b32 v[8:9], v14 offset1:32
	ds_read2st64_b32 v[10:11], v14 offset0:64 offset1:96
	ds_read2st64_b32 v[12:13], v14 offset0:128 offset1:160
	ds_read2st64_b32 v[14:15], v14 offset0:192 offset1:224
	v_mad_u64_u32 v[16:17], s[14:15], v6, s23, v[4:5]
	v_mad_i32_i24 v17, v7, s23, v17
	v_lshl_add_u64 v[6:7], v[16:17], 0, v[2:3]
	s_waitcnt vmcnt(0) lgkmcnt(0)
	v_add_f32_e32 v2, v18, v8
	v_add_f32_e32 v2, v2, v9
	v_add_f32_e32 v2, v2, v10
	v_add_f32_e32 v2, v2, v11
	v_add_f32_e32 v2, v2, v12
	v_add_f32_e32 v2, v2, v13
	v_add_f32_e32 v2, v2, v14
	v_add_f32_e32 v2, v2, v15
	global_store_dword v[6:7], v2, off
	v_mbcnt_lo_u32_b32 v2, -1, 0
	v_mbcnt_hi_u32_b32 v2, -1, v2
	s_nop 0
	v_and_b32_e32 v8, 63, v2
	v_or_b32_e32 v6, s33, v8
	v_ashrrev_i32_e32 v7, 31, v6
	v_lshl_add_u64 v[6:7], v[6:7], 2, s[16:17]
	flat_load_dword v18, v[6:7]
	v_add_u32_e32 v6, s3, v2
	v_and_b32_e32 v7, 0x3fffffc0, v6
	v_ashrrev_i32_e32 v6, 6, v6
	v_lshlrev_b32_e32 v2, 2, v8
	v_lshlrev_b32_e32 v8, 2, v7
	v_ashrrev_i32_e32 v7, 31, v6
	v_add3_u32 v14, 0, v8, v2
	v_lshl_add_u64 v[6:7], s[10:11], 0, v[6:7]
	ds_read2st64_b32 v[8:9], v14 offset1:32
	ds_read2st64_b32 v[10:11], v14 offset0:64 offset1:96
	ds_read2st64_b32 v[12:13], v14 offset0:128 offset1:160
	ds_read2st64_b32 v[14:15], v14 offset0:192 offset1:224
	v_mad_u64_u32 v[16:17], s[14:15], v6, s23, v[4:5]
	v_mad_i32_i24 v17, v7, s23, v17
	v_lshl_add_u64 v[6:7], v[16:17], 0, v[2:3]
	s_waitcnt vmcnt(0) lgkmcnt(0)
	v_add_f32_e32 v2, v18, v8
	v_add_f32_e32 v2, v2, v9
	v_add_f32_e32 v2, v2, v10
	v_add_f32_e32 v2, v2, v11
	v_add_f32_e32 v2, v2, v12
	v_add_f32_e32 v2, v2, v13
	v_add_f32_e32 v2, v2, v14
	v_add_f32_e32 v2, v2, v15
	global_store_dword v[6:7], v2, off
	v_mbcnt_lo_u32_b32 v2, -1, 0
	v_mbcnt_hi_u32_b32 v2, -1, v2
	s_nop 0
	v_and_b32_e32 v8, 63, v2
	v_or_b32_e32 v6, s33, v8
	v_ashrrev_i32_e32 v7, 31, v6
	v_lshl_add_u64 v[6:7], v[6:7], 2, s[16:17]
	flat_load_dword v16, v[6:7]
	v_add_u32_e32 v6, s18, v2
	v_and_b32_e32 v7, 0x3fffffc0, v6
	v_ashrrev_i32_e32 v6, 6, v6
	v_lshlrev_b32_e32 v2, 2, v8
	v_lshlrev_b32_e32 v8, 2, v7
	v_ashrrev_i32_e32 v7, 31, v6
	v_add3_u32 v14, 0, v8, v2
	v_lshl_add_u64 v[6:7], s[10:11], 0, v[6:7]
	ds_read2st64_b32 v[8:9], v14 offset1:32
	ds_read2st64_b32 v[10:11], v14 offset0:64 offset1:96
	ds_read2st64_b32 v[12:13], v14 offset0:128 offset1:160
	ds_read2st64_b32 v[14:15], v14 offset0:192 offset1:224
	v_mad_u64_u32 v[4:5], s[10:11], v6, s23, v[4:5]
	v_mad_i32_i24 v5, v7, s23, v5
	v_lshl_add_u64 v[4:5], v[4:5], 0, v[2:3]
	s_waitcnt vmcnt(0) lgkmcnt(0)
	v_add_f32_e32 v2, v16, v8
	v_add_f32_e32 v2, v2, v9
	v_add_f32_e32 v2, v2, v10
	v_add_f32_e32 v2, v2, v11
	v_add_f32_e32 v2, v2, v12
	v_add_f32_e32 v2, v2, v13
	v_add_f32_e32 v2, v2, v14
	v_add_f32_e32 v2, v2, v15
	global_store_dword v[4:5], v2, off
	s_barrier
	s_cbranch_scc0 .LBB0_8
